# P1 epilogue: both bf16 halves converted first, ten ds_bpermutes issued together and drained with two counted waits (one exposed round trip per block instead of two), on top of v020
# baseline (speedup 1.0000x reference)
; DEVI unsigned pk_bf16(float lo, float hi) { const f32x2_t v = {lo, hi}; const bf16x2_t b = __builtin_convertvector(v, bf16x2_t); return __builtin_bit_cast(unsigned, b); }
;     DEVI void operator()(const f32x4 (&acc)[2][2][4][2], const pg8::Unit& u, int wr, int wc, int l15, int g) const {
;     ...
;         const float* RC = (const float*)(p.ws + W_ROPE); const float* RS = RC + 4096 * 8;
;         const bool wb = bdst && (!bprompt || prompt);
;     ...
;             if (wb) {
;                 bf16_t* bp = bdst + (size_t)tok * bw + colo + 16 * (g & 1) + 8 * (g >> 1);
; #pragma unroll
;                 for (int pr = 0; pr < 2; ++pr) {
;                     const unsigned x0 = pk_bf16(v[2 * pr][0], v[2 * pr][1]), x1 = pk_bf16(v[2 * pr][2], v[2 * pr][3]);
;                     const unsigned y0 = pk_bf16(v[2 * pr + 1][0], v[2 * pr + 1][1]), y1 = pk_bf16(v[2 * pr + 1][2], v[2 * pr + 1][3]);
;                     const auto r0 = __builtin_amdgcn_permlane16_swap(x0, y0, false, false);
;                     const auto r1 = __builtin_amdgcn_permlane16_swap(x1, y1, false, false);
;                     const u32x4 o = (u32x4){r0[0], r1[0], r0[1], r1[1]};
;                     *(u32x4*)(bp + 32 * pr) = o;
;                 }
.LBB0_230:
	s_cmp_lg_u64 s[14:15], 0
	s_cselect_b64 s[68:69], -1, 0
	s_and_b64 s[16:17], s[68:69], s[16:17]
	s_lshl_b64 s[12:13], s[12:13], 1
	s_add_u32 s12, s14, s12
	s_addc_u32 s13, s15, s13
	v_mov_b32_e32 v215, v201
	v_lshl_add_u64 v[116:117], s[12:13], 0, v[214:215]
	v_mov_b32_e32 v217, v201
	v_cndmask_b32_e64 v118, 0, 1, s[16:17]
	v_cmp_ne_u32_e64 s[12:13], 1, v118
	s_andn2_b64 vcc, exec, s[16:17]
	v_lshl_add_u64 v[222:223], v[116:117], 0, v[216:217]
	s_cbranch_vccnz .LBB0_232
	v_ashrrev_i32_e32 v116, 31, v218
	v_mul_lo_u32 v118, s63, v218
	v_mul_lo_u32 v119, s62, v116
	v_mad_u64_u32 v[116:117], s[14:15], s62, v218, 0
	v_add3_u32 v117, v117, v119, v118
	v_lshl_add_u64 v[120:121], v[116:117], 1, v[222:223]
	v_cvt_pk_bf16_f32 v116, v132, v133
	v_cvt_pk_bf16_f32 v117, v134, v135
	v_cvt_pk_bf16_f32 v118, v136, v137
	v_cvt_pk_bf16_f32 v119, v138, v139
	s_nop 0
	v_permlane16_swap_b32_e32 v116, v118
	v_permlane16_swap_b32_e32 v117, v119
	v_cvt_pk_bf16_f32 v248, v140, v141
	v_cvt_pk_bf16_f32 v249, v142, v143
	v_cvt_pk_bf16_f32 v250, v144, v145
	v_cvt_pk_bf16_f32 v251, v146, v147
	s_nop 1
	v_permlane16_swap_b32_e32 v248, v250
	v_permlane16_swap_b32_e32 v249, v251
	ds_bpermute_b32 v236, v239, v120
	ds_bpermute_b32 v237, v239, v121
	ds_bpermute_b32 v240, v239, v116
	ds_bpermute_b32 v241, v239, v117
	ds_bpermute_b32 v242, v239, v118
	ds_bpermute_b32 v243, v239, v119
	ds_bpermute_b32 v244, v239, v248
	ds_bpermute_b32 v245, v239, v249
	ds_bpermute_b32 v246, v239, v250
	ds_bpermute_b32 v247, v239, v251
	s_waitcnt lgkmcnt(4)
	global_store_dwordx4 v[236:237], v[240:243], off
	s_waitcnt lgkmcnt(0)
	global_store_dwordx4 v[236:237], v[244:247], off offset:64

; DEVI unsigned pk_bf16(float lo, float hi) { const f32x2_t v = {lo, hi}; const bf16x2_t b = __builtin_convertvector(v, bf16x2_t); return __builtin_bit_cast(unsigned, b); }
;     DEVI void operator()(const f32x4 (&acc)[2][2][4][2], const pg8::Unit& u, int wr, int wc, int l15, int g) const {
;     ...
;             if (wb) {
;                 bf16_t* bp = bdst + (size_t)tok * bw + colo + 16 * (g & 1) + 8 * (g >> 1);
; #pragma unroll
;                 for (int pr = 0; pr < 2; ++pr) {
;                     const unsigned x0 = pk_bf16(v[2 * pr][0], v[2 * pr][1]), x1 = pk_bf16(v[2 * pr][2], v[2 * pr][3]);
;                     const unsigned y0 = pk_bf16(v[2 * pr + 1][0], v[2 * pr + 1][1]), y1 = pk_bf16(v[2 * pr + 1][2], v[2 * pr + 1][3]);
;                     const auto r0 = __builtin_amdgcn_permlane16_swap(x0, y0, false, false);
;                     const auto r1 = __builtin_amdgcn_permlane16_swap(x1, y1, false, false);
;                     const u32x4 o = (u32x4){r0[0], r1[0], r0[1], r1[1]};
;                     *(u32x4*)(bp + 32 * pr) = o;
;                 }
.LBB0_245:
	s_and_b64 vcc, exec, s[12:13]
	s_cbranch_vccnz .LBB0_247
	v_ashrrev_i32_e32 v101, 31, v100
	v_mul_lo_u32 v102, s63, v100
	v_mul_lo_u32 v103, s62, v101
	v_mad_u64_u32 v[100:101], s[68:69], s62, v100, 0
	v_add3_u32 v101, v101, v103, v102
	v_lshl_add_u64 v[104:105], v[100:101], 1, v[222:223]
	v_cvt_pk_bf16_f32 v100, v132, v133
	v_cvt_pk_bf16_f32 v101, v134, v135
	v_cvt_pk_bf16_f32 v102, v136, v137
	v_cvt_pk_bf16_f32 v103, v138, v139
	s_nop 0
	v_permlane16_swap_b32_e32 v100, v102
	v_permlane16_swap_b32_e32 v101, v103
	v_cvt_pk_bf16_f32 v248, v140, v141
	v_cvt_pk_bf16_f32 v249, v142, v143
	v_cvt_pk_bf16_f32 v250, v144, v145
	v_cvt_pk_bf16_f32 v251, v146, v147
	s_nop 1
	v_permlane16_swap_b32_e32 v248, v250
	v_permlane16_swap_b32_e32 v249, v251
	ds_bpermute_b32 v236, v239, v104
	ds_bpermute_b32 v237, v239, v105
	ds_bpermute_b32 v240, v239, v100
	ds_bpermute_b32 v241, v239, v101
	ds_bpermute_b32 v242, v239, v102
	ds_bpermute_b32 v243, v239, v103
	ds_bpermute_b32 v244, v239, v248
	ds_bpermute_b32 v245, v239, v249
	ds_bpermute_b32 v246, v239, v250
	ds_bpermute_b32 v247, v239, v251
	s_waitcnt lgkmcnt(4)
	global_store_dwordx4 v[236:237], v[240:243], off
	s_waitcnt lgkmcnt(0)
	global_store_dwordx4 v[236:237], v[244:247], off offset:64

; DEVI unsigned pk_bf16(float lo, float hi) { const f32x2_t v = {lo, hi}; const bf16x2_t b = __builtin_convertvector(v, bf16x2_t); return __builtin_bit_cast(unsigned, b); }
;     DEVI void operator()(const f32x4 (&acc)[2][2][4][2], const pg8::Unit& u, int wr, int wc, int l15, int g) const {
;     ...
;             if (wb) {
;                 bf16_t* bp = bdst + (size_t)tok * bw + colo + 16 * (g & 1) + 8 * (g >> 1);
; #pragma unroll
;                 for (int pr = 0; pr < 2; ++pr) {
;                     const unsigned x0 = pk_bf16(v[2 * pr][0], v[2 * pr][1]), x1 = pk_bf16(v[2 * pr][2], v[2 * pr][3]);
;                     const unsigned y0 = pk_bf16(v[2 * pr + 1][0], v[2 * pr + 1][1]), y1 = pk_bf16(v[2 * pr + 1][2], v[2 * pr + 1][3]);
;                     const auto r0 = __builtin_amdgcn_permlane16_swap(x0, y0, false, false);
;                     const auto r1 = __builtin_amdgcn_permlane16_swap(x1, y1, false, false);
;                     const u32x4 o = (u32x4){r0[0], r1[0], r0[1], r1[1]};
;                     *(u32x4*)(bp + 32 * pr) = o;
;                 }
.LBB0_260:
	s_and_b64 vcc, exec, s[12:13]
	s_cbranch_vccnz .LBB0_262
	v_ashrrev_i32_e32 v85, 31, v84
	v_mul_lo_u32 v86, s63, v84
	v_mul_lo_u32 v87, s62, v85
	v_mad_u64_u32 v[84:85], s[68:69], s62, v84, 0
	v_add3_u32 v85, v85, v87, v86
	v_lshl_add_u64 v[88:89], v[84:85], 1, v[222:223]
	v_cvt_pk_bf16_f32 v84, v132, v133
	v_cvt_pk_bf16_f32 v85, v134, v135
	v_cvt_pk_bf16_f32 v86, v136, v137
	v_cvt_pk_bf16_f32 v87, v138, v139
	s_nop 0
	v_permlane16_swap_b32_e32 v84, v86
	v_permlane16_swap_b32_e32 v85, v87
	v_cvt_pk_bf16_f32 v248, v140, v141
	v_cvt_pk_bf16_f32 v249, v142, v143
	v_cvt_pk_bf16_f32 v250, v144, v145
	v_cvt_pk_bf16_f32 v251, v146, v147
	s_nop 1
	v_permlane16_swap_b32_e32 v248, v250
	v_permlane16_swap_b32_e32 v249, v251
	ds_bpermute_b32 v236, v239, v88
	ds_bpermute_b32 v237, v239, v89
	ds_bpermute_b32 v240, v239, v84
	ds_bpermute_b32 v241, v239, v85
	ds_bpermute_b32 v242, v239, v86
	ds_bpermute_b32 v243, v239, v87
	ds_bpermute_b32 v244, v239, v248
	ds_bpermute_b32 v245, v239, v249
	ds_bpermute_b32 v246, v239, v250
	ds_bpermute_b32 v247, v239, v251
	s_waitcnt lgkmcnt(4)
	global_store_dwordx4 v[236:237], v[240:243], off
	s_waitcnt lgkmcnt(0)
	global_store_dwordx4 v[236:237], v[244:247], off offset:64

; DEVI unsigned pk_bf16(float lo, float hi) { const f32x2_t v = {lo, hi}; const bf16x2_t b = __builtin_convertvector(v, bf16x2_t); return __builtin_bit_cast(unsigned, b); }
;     DEVI void operator()(const f32x4 (&acc)[2][2][4][2], const pg8::Unit& u, int wr, int wc, int l15, int g) const {
;     ...
;             if (wb) {
;                 bf16_t* bp = bdst + (size_t)tok * bw + colo + 16 * (g & 1) + 8 * (g >> 1);
; #pragma unroll
;                 for (int pr = 0; pr < 2; ++pr) {
;                     const unsigned x0 = pk_bf16(v[2 * pr][0], v[2 * pr][1]), x1 = pk_bf16(v[2 * pr][2], v[2 * pr][3]);
;                     const unsigned y0 = pk_bf16(v[2 * pr + 1][0], v[2 * pr + 1][1]), y1 = pk_bf16(v[2 * pr + 1][2], v[2 * pr + 1][3]);
;                     const auto r0 = __builtin_amdgcn_permlane16_swap(x0, y0, false, false);
;                     const auto r1 = __builtin_amdgcn_permlane16_swap(x1, y1, false, false);
;                     const u32x4 o = (u32x4){r0[0], r1[0], r0[1], r1[1]};
;                     *(u32x4*)(bp + 32 * pr) = o;
;                 }
.LBB0_275:
	s_and_b64 vcc, exec, s[12:13]
	s_cbranch_vccnz .LBB0_277
	v_ashrrev_i32_e32 v69, 31, v68
	v_mul_lo_u32 v70, s63, v68
	v_mul_lo_u32 v71, s62, v69
	v_mad_u64_u32 v[68:69], s[68:69], s62, v68, 0
	v_add3_u32 v69, v69, v71, v70
	v_lshl_add_u64 v[72:73], v[68:69], 1, v[222:223]
	v_cvt_pk_bf16_f32 v68, v132, v133
	v_cvt_pk_bf16_f32 v69, v134, v135
	v_cvt_pk_bf16_f32 v70, v136, v137
	v_cvt_pk_bf16_f32 v71, v138, v139
	s_nop 0
	v_permlane16_swap_b32_e32 v68, v70
	v_permlane16_swap_b32_e32 v69, v71
	v_cvt_pk_bf16_f32 v248, v140, v141
	v_cvt_pk_bf16_f32 v249, v142, v143
	v_cvt_pk_bf16_f32 v250, v144, v145
	v_cvt_pk_bf16_f32 v251, v146, v147
	s_nop 1
	v_permlane16_swap_b32_e32 v248, v250
	v_permlane16_swap_b32_e32 v249, v251
	ds_bpermute_b32 v236, v239, v72
	ds_bpermute_b32 v237, v239, v73
	ds_bpermute_b32 v240, v239, v68
	ds_bpermute_b32 v241, v239, v69
	ds_bpermute_b32 v242, v239, v70
	ds_bpermute_b32 v243, v239, v71
	ds_bpermute_b32 v244, v239, v248
	ds_bpermute_b32 v245, v239, v249
	ds_bpermute_b32 v246, v239, v250
	ds_bpermute_b32 v247, v239, v251
	s_waitcnt lgkmcnt(4)
	global_store_dwordx4 v[236:237], v[240:243], off
	s_waitcnt lgkmcnt(0)
	global_store_dwordx4 v[236:237], v[244:247], off offset:64

; DEVI unsigned pk_bf16(float lo, float hi) { const f32x2_t v = {lo, hi}; const bf16x2_t b = __builtin_convertvector(v, bf16x2_t); return __builtin_bit_cast(unsigned, b); }
;     DEVI void operator()(const f32x4 (&acc)[2][2][4][2], const pg8::Unit& u, int wr, int wc, int l15, int g) const {
;     ...
;             if (wb) {
;                 bf16_t* bp = bdst + (size_t)tok * bw + colo + 16 * (g & 1) + 8 * (g >> 1);
; #pragma unroll
;                 for (int pr = 0; pr < 2; ++pr) {
;                     const unsigned x0 = pk_bf16(v[2 * pr][0], v[2 * pr][1]), x1 = pk_bf16(v[2 * pr][2], v[2 * pr][3]);
;                     const unsigned y0 = pk_bf16(v[2 * pr + 1][0], v[2 * pr + 1][1]), y1 = pk_bf16(v[2 * pr + 1][2], v[2 * pr + 1][3]);
;                     const auto r0 = __builtin_amdgcn_permlane16_swap(x0, y0, false, false);
;                     const auto r1 = __builtin_amdgcn_permlane16_swap(x1, y1, false, false);
;                     const u32x4 o = (u32x4){r0[0], r1[0], r0[1], r1[1]};
;                     *(u32x4*)(bp + 32 * pr) = o;
;                 }
.LBB0_292:
	s_and_b64 vcc, exec, s[12:13]
	s_cbranch_vccnz .LBB0_294
	v_ashrrev_i32_e32 v52, 31, v71
	v_mul_lo_u32 v54, s63, v71
	v_mul_lo_u32 v55, s62, v52
	v_mad_u64_u32 v[52:53], s[68:69], s62, v71, 0
	v_add3_u32 v53, v53, v55, v54
	v_lshl_add_u64 v[56:57], v[52:53], 1, v[222:223]
	v_cvt_pk_bf16_f32 v52, v132, v133
	v_cvt_pk_bf16_f32 v53, v134, v135
	v_cvt_pk_bf16_f32 v54, v136, v137
	v_cvt_pk_bf16_f32 v55, v138, v139
	s_nop 0
	v_permlane16_swap_b32_e32 v52, v54
	v_permlane16_swap_b32_e32 v53, v55
	v_cvt_pk_bf16_f32 v248, v140, v141
	v_cvt_pk_bf16_f32 v249, v142, v143
	v_cvt_pk_bf16_f32 v250, v144, v145
	v_cvt_pk_bf16_f32 v251, v146, v147
	s_nop 1
	v_permlane16_swap_b32_e32 v248, v250
	v_permlane16_swap_b32_e32 v249, v251
	ds_bpermute_b32 v236, v239, v56
	ds_bpermute_b32 v237, v239, v57
	ds_bpermute_b32 v240, v239, v52
	ds_bpermute_b32 v241, v239, v53
	ds_bpermute_b32 v242, v239, v54
	ds_bpermute_b32 v243, v239, v55
	ds_bpermute_b32 v244, v239, v248
	ds_bpermute_b32 v245, v239, v249
	ds_bpermute_b32 v246, v239, v250
	ds_bpermute_b32 v247, v239, v251
	s_waitcnt lgkmcnt(4)
	global_store_dwordx4 v[236:237], v[240:243], off
	s_waitcnt lgkmcnt(0)
	global_store_dwordx4 v[236:237], v[244:247], off offset:64

; DEVI unsigned pk_bf16(float lo, float hi) { const f32x2_t v = {lo, hi}; const bf16x2_t b = __builtin_convertvector(v, bf16x2_t); return __builtin_bit_cast(unsigned, b); }
;     DEVI void operator()(const f32x4 (&acc)[2][2][4][2], const pg8::Unit& u, int wr, int wc, int l15, int g) const {
;     ...
;             if (wb) {
;                 bf16_t* bp = bdst + (size_t)tok * bw + colo + 16 * (g & 1) + 8 * (g >> 1);
; #pragma unroll
;                 for (int pr = 0; pr < 2; ++pr) {
;                     const unsigned x0 = pk_bf16(v[2 * pr][0], v[2 * pr][1]), x1 = pk_bf16(v[2 * pr][2], v[2 * pr][3]);
;                     const unsigned y0 = pk_bf16(v[2 * pr + 1][0], v[2 * pr + 1][1]), y1 = pk_bf16(v[2 * pr + 1][2], v[2 * pr + 1][3]);
;                     const auto r0 = __builtin_amdgcn_permlane16_swap(x0, y0, false, false);
;                     const auto r1 = __builtin_amdgcn_permlane16_swap(x1, y1, false, false);
;                     const u32x4 o = (u32x4){r0[0], r1[0], r0[1], r1[1]};
;                     *(u32x4*)(bp + 32 * pr) = o;
;                 }
.LBB0_307:
	s_and_b64 vcc, exec, s[12:13]
	s_cbranch_vccnz .LBB0_309
	v_ashrrev_i32_e32 v36, 31, v70
	v_mul_lo_u32 v38, s63, v70
	v_mul_lo_u32 v39, s62, v36
	v_mad_u64_u32 v[36:37], s[68:69], s62, v70, 0
	v_add3_u32 v37, v37, v39, v38
	v_lshl_add_u64 v[40:41], v[36:37], 1, v[222:223]
	v_cvt_pk_bf16_f32 v36, v132, v133
	v_cvt_pk_bf16_f32 v37, v134, v135
	v_cvt_pk_bf16_f32 v38, v136, v137
	v_cvt_pk_bf16_f32 v39, v138, v139
	s_nop 0
	v_permlane16_swap_b32_e32 v36, v38
	v_permlane16_swap_b32_e32 v37, v39
	v_cvt_pk_bf16_f32 v248, v140, v141
	v_cvt_pk_bf16_f32 v249, v142, v143
	v_cvt_pk_bf16_f32 v250, v144, v145
	v_cvt_pk_bf16_f32 v251, v146, v147
	s_nop 1
	v_permlane16_swap_b32_e32 v248, v250
	v_permlane16_swap_b32_e32 v249, v251
	ds_bpermute_b32 v236, v239, v40
	ds_bpermute_b32 v237, v239, v41
	ds_bpermute_b32 v240, v239, v36
	ds_bpermute_b32 v241, v239, v37
	ds_bpermute_b32 v242, v239, v38
	ds_bpermute_b32 v243, v239, v39
	ds_bpermute_b32 v244, v239, v248
	ds_bpermute_b32 v245, v239, v249
	ds_bpermute_b32 v246, v239, v250
	ds_bpermute_b32 v247, v239, v251
	s_waitcnt lgkmcnt(4)
	global_store_dwordx4 v[236:237], v[240:243], off
	s_waitcnt lgkmcnt(0)
	global_store_dwordx4 v[236:237], v[244:247], off offset:64

; DEVI unsigned pk_bf16(float lo, float hi) { const f32x2_t v = {lo, hi}; const bf16x2_t b = __builtin_convertvector(v, bf16x2_t); return __builtin_bit_cast(unsigned, b); }
;     DEVI void operator()(const f32x4 (&acc)[2][2][4][2], const pg8::Unit& u, int wr, int wc, int l15, int g) const {
;     ...
;             if (wb) {
;                 bf16_t* bp = bdst + (size_t)tok * bw + colo + 16 * (g & 1) + 8 * (g >> 1);
; #pragma unroll
;                 for (int pr = 0; pr < 2; ++pr) {
;                     const unsigned x0 = pk_bf16(v[2 * pr][0], v[2 * pr][1]), x1 = pk_bf16(v[2 * pr][2], v[2 * pr][3]);
;                     const unsigned y0 = pk_bf16(v[2 * pr + 1][0], v[2 * pr + 1][1]), y1 = pk_bf16(v[2 * pr + 1][2], v[2 * pr + 1][3]);
;                     const auto r0 = __builtin_amdgcn_permlane16_swap(x0, y0, false, false);
;                     const auto r1 = __builtin_amdgcn_permlane16_swap(x1, y1, false, false);
;                     const u32x4 o = (u32x4){r0[0], r1[0], r0[1], r1[1]};
;                     *(u32x4*)(bp + 32 * pr) = o;
;                 }
.LBB0_322:
	s_and_b64 vcc, exec, s[12:13]
	s_cbranch_vccnz .LBB0_324
	v_ashrrev_i32_e32 v20, 31, v69
	v_mul_lo_u32 v22, s63, v69
	v_mul_lo_u32 v23, s62, v20
	v_mad_u64_u32 v[20:21], s[68:69], s62, v69, 0
	v_add3_u32 v21, v21, v23, v22
	v_lshl_add_u64 v[24:25], v[20:21], 1, v[222:223]
	v_cvt_pk_bf16_f32 v20, v132, v133
	v_cvt_pk_bf16_f32 v21, v134, v135
	v_cvt_pk_bf16_f32 v22, v136, v137
	v_cvt_pk_bf16_f32 v23, v138, v139
	s_nop 0
	v_permlane16_swap_b32_e32 v20, v22
	v_permlane16_swap_b32_e32 v21, v23
	v_cvt_pk_bf16_f32 v248, v140, v141
	v_cvt_pk_bf16_f32 v249, v142, v143
	v_cvt_pk_bf16_f32 v250, v144, v145
	v_cvt_pk_bf16_f32 v251, v146, v147
	s_nop 1
	v_permlane16_swap_b32_e32 v248, v250
	v_permlane16_swap_b32_e32 v249, v251
	ds_bpermute_b32 v236, v239, v24
	ds_bpermute_b32 v237, v239, v25
	ds_bpermute_b32 v240, v239, v20
	ds_bpermute_b32 v241, v239, v21
	ds_bpermute_b32 v242, v239, v22
	ds_bpermute_b32 v243, v239, v23
	ds_bpermute_b32 v244, v239, v248
	ds_bpermute_b32 v245, v239, v249
	ds_bpermute_b32 v246, v239, v250
	ds_bpermute_b32 v247, v239, v251
	s_waitcnt lgkmcnt(4)
	global_store_dwordx4 v[236:237], v[240:243], off
	s_waitcnt lgkmcnt(0)
	global_store_dwordx4 v[236:237], v[244:247], off offset:64

; DEVI unsigned pk_bf16(float lo, float hi) { const f32x2_t v = {lo, hi}; const bf16x2_t b = __builtin_convertvector(v, bf16x2_t); return __builtin_bit_cast(unsigned, b); }
;     DEVI void operator()(const f32x4 (&acc)[2][2][4][2], const pg8::Unit& u, int wr, int wc, int l15, int g) const {
;     ...
;             if (wb) {
;                 bf16_t* bp = bdst + (size_t)tok * bw + colo + 16 * (g & 1) + 8 * (g >> 1);
; #pragma unroll
;                 for (int pr = 0; pr < 2; ++pr) {
;                     const unsigned x0 = pk_bf16(v[2 * pr][0], v[2 * pr][1]), x1 = pk_bf16(v[2 * pr][2], v[2 * pr][3]);
;                     const unsigned y0 = pk_bf16(v[2 * pr + 1][0], v[2 * pr + 1][1]), y1 = pk_bf16(v[2 * pr + 1][2], v[2 * pr + 1][3]);
;                     const auto r0 = __builtin_amdgcn_permlane16_swap(x0, y0, false, false);
;                     const auto r1 = __builtin_amdgcn_permlane16_swap(x1, y1, false, false);
;                     const u32x4 o = (u32x4){r0[0], r1[0], r0[1], r1[1]};
;                     *(u32x4*)(bp + 32 * pr) = o;
;                 }
.LBB0_337:
	s_and_b64 vcc, exec, s[12:13]
	s_cbranch_vccnz .LBB0_339
	v_ashrrev_i32_e32 v4, 31, v68
	v_mul_lo_u32 v6, s63, v68
	v_mul_lo_u32 v7, s62, v4
	v_mad_u64_u32 v[4:5], s[4:5], s62, v68, 0
	v_add3_u32 v5, v5, v7, v6
	v_lshl_add_u64 v[8:9], v[4:5], 1, v[222:223]
	v_cvt_pk_bf16_f32 v4, v132, v133
	v_cvt_pk_bf16_f32 v5, v134, v135
	v_cvt_pk_bf16_f32 v6, v136, v137
	v_cvt_pk_bf16_f32 v7, v138, v139
	s_nop 0
	v_permlane16_swap_b32_e32 v4, v6
	v_permlane16_swap_b32_e32 v5, v7
	v_cvt_pk_bf16_f32 v248, v140, v141
	v_cvt_pk_bf16_f32 v249, v142, v143
	v_cvt_pk_bf16_f32 v250, v144, v145
	v_cvt_pk_bf16_f32 v251, v146, v147
	s_nop 1
	v_permlane16_swap_b32_e32 v248, v250
	v_permlane16_swap_b32_e32 v249, v251
	ds_bpermute_b32 v236, v239, v8
	ds_bpermute_b32 v237, v239, v9
	ds_bpermute_b32 v240, v239, v4
	ds_bpermute_b32 v241, v239, v5
	ds_bpermute_b32 v242, v239, v6
	ds_bpermute_b32 v243, v239, v7
	ds_bpermute_b32 v244, v239, v248
	ds_bpermute_b32 v245, v239, v249
	ds_bpermute_b32 v246, v239, v250
	ds_bpermute_b32 v247, v239, v251
	s_waitcnt lgkmcnt(4)
	global_store_dwordx4 v[236:237], v[240:243], off
	s_waitcnt lgkmcnt(0)
	global_store_dwordx4 v[236:237], v[244:247], off offset:64
